# dn_prep stage 1: unmasked copy of the conv sequence for chunks n>0 (no zero-init, no per-load exec masks), chosen per item
# speedup vs baseline: 1.0009x; 1.0009x over previous
; __device__ __forceinline__ void dn_prep_item(const Args& a, LAS unsigned char* lds, int item, int tid, int wave, int lane, int& cwh, int next_item) {
;     ...
;     for (int r = 0; r < 6; ++r) { const int task = tid + NTHR * r, which = task >> 10, i = (task & 1023) >> 4, gq = task & 15;
;         const int col = 1024 + which * 512 + h * 128 + 8 * gq;
;         v4u xv[4];
; #pragma unroll
;         for (int jj = 0; jj < 4; ++jj) { const int pos = n * 64 + i - 3 + jj; xv[jj] = (v4u){0u, 0u, 0u, 0u};
;             if (pos >= 0) xv[jj] = *(const v4u*)(P + (size_t)(b * T + pos) * NIN + col); }
.LBB0_746:
	s_cmp_gt_i32 s86, -1
	s_cbranch_scc1 .Ls1_fast
	v_add_u32_e32 v0, 0, v220
	v_lshrrev_b32_e32 v43, 10, v41
	v_and_b32_e32 v42, 63, v0
	v_lshl_add_u32 v1, v43, 9, v36
	v_add_u32_e32 v0, s86, v42
	v_cmp_lt_i32_e32 vcc, -1, v0
	v_mov_b32_e32 v8, 0
	v_lshlrev_b32_e32 v56, 1, v1
	v_mov_b32_e32 v16, 0
	v_mov_b32_e32 v17, 0
	v_mov_b32_e32 v18, 0
	v_mov_b32_e32 v19, 0
	s_and_saveexec_b64 s[22:23], vcc
	v_add_u32_e32 v1, s41, v0
	v_mov_b64_e32 v[2:3], s[10:11]
	v_mad_u64_u32 v[2:3], vcc, v1, s25, v[2:3]
	v_lshl_add_u64 v[2:3], v[2:3], 0, v[56:57]
	global_load_dwordx4 v[16:19], v[2:3], off

; #define LAS __attribute__((address_space(3)))
; __device__ __forceinline__ float lo_bf(unsigned w) { return __uint_as_float(w << 16); }
; __device__ __forceinline__ float hi_bf(unsigned w) { return __uint_as_float(w & 0xffff0000u); }
; __device__ __forceinline__ unsigned pk2(float lo, float hi) { const f32x2_t v = {lo, hi}; const bf16x2_t b = __builtin_convertvector(v, bf16x2_t); return __builtin_bit_cast(unsigned, b); }
; __device__ __forceinline__ float silu_(float x) { return x * sigm(x); }
; __device__ __forceinline__ void dn_prep_item(const Args& a, LAS unsigned char* lds, int item, int tid, int wave, int lane, int& cwh, int next_item) {
;     ...
;     for (int r = 0; r < 6; ++r) { const int task = tid + NTHR * r, which = task >> 10, i = (task & 1023) >> 4, gq = task & 15;
;         const int col = 1024 + which * 512 + h * 128 + 8 * gq;
;         v4u xv[4];
; #pragma unroll
;         for (int jj = 0; jj < 4; ++jj) { const int pos = n * 64 + i - 3 + jj; xv[jj] = (v4u){0u, 0u, 0u, 0u};
;             if (pos >= 0) xv[jj] = *(const v4u*)(P + (size_t)(b * T + pos) * NIN + col); }
;         float o[8];
; #pragma unroll
;         for (int q = 0; q < 8; ++q) o[q] = 0.f;
; #pragma unroll
;         for (int jj = 0; jj < 4; ++jj) { const v4u v = xv[jj];
;             const f32x4 w0 = *(const LAS f32x4*)(cwl + (which * 4 + jj) * 128 + 8 * gq), w1 = *(const LAS f32x4*)(cwl + (which * 4 + jj) * 128 + 8 * gq + 4);
;             o[0] += w0[0] * lo_bf(v.x); o[1] += w0[1] * hi_bf(v.x); o[2] += w0[2] * lo_bf(v.y); o[3] += w0[3] * hi_bf(v.y);
;             o[4] += w1[0] * lo_bf(v.z); o[5] += w1[1] * hi_bf(v.z); o[6] += w1[2] * lo_bf(v.w); o[7] += w1[3] * hi_bf(v.w); }
;         float s = 0.f;
; #pragma unroll
;         for (int q = 0; q < 8; ++q) { o[q] = silu_(o[q]); s += o[q] * o[q]; }
;         s += __shfl_xor(s, 1); s += __shfl_xor(s, 2); s += __shfl_xor(s, 4); s += __shfl_xor(s, 8);
;         const float inv = which == 2 ? 1.0f : rsqrtf(s + EPS) * (which == 0 ? 0.08838834764831845f : 1.0f);
;         v4u w; w.x = pk2(o[0] * inv, o[1] * inv); w.y = pk2(o[2] * inv, o[3] * inv); w.z = pk2(o[4] * inv, o[5] * inv); w.w = pk2(o[6] * inv, o[7] * inv);
;         *(LAS v4u*)(lds + (which == 0 ? L_QS : which == 1 ? L_KH : L_V) + i * KS_ + 16 * gq) = w;
.Ls1t5_745:
	s_or_b64 exec, exec, s[22:23]
	s_waitcnt lgkmcnt(0)
	v_pk_mul_f32 v[90:91], v[32:33], v[88:89] op_sel_hi:[1,0]
	v_pk_mul_f32 v[92:93], v[92:93], v[88:89] op_sel_hi:[1,0]
	v_pk_mul_f32 v[0:1], v[0:1], v[88:89] op_sel_hi:[1,0]
	v_cvt_pk_bf16_f32 v90, v90, v91
	v_cvt_pk_bf16_f32 v91, v92, v93
	v_cvt_pk_bf16_f32 v92, v0, v1
	v_pk_mul_f32 v[0:1], v[2:3], v[88:89] op_sel_hi:[1,0]
	v_cmp_eq_u32_e32 vcc, 1, v109
	v_cvt_pk_bf16_f32 v93, v0, v1
	v_mul_u32_u24_e32 v1, 0x110, v108
	v_cndmask_b32_e64 v0, v188, 0, vcc
	v_add_u32_e32 v0, 0, v0
	v_add3_u32 v0, v0, v1, v151
	ds_write_b128 v0, v[90:93]
	s_branch .LBB0_770
.Ls1_fast:
	v_add_u32_e32 v0, 0, v220
	v_lshrrev_b32_e32 v43, 10, v41
	v_and_b32_e32 v42, 63, v0
	v_lshl_add_u32 v1, v43, 9, v36
	v_add_u32_e32 v0, s86, v42
	v_lshlrev_b32_e32 v56, 1, v1
	v_add_u32_e32 v1, s41, v0
	v_mov_b64_e32 v[2:3], s[10:11]
	v_mad_u64_u32 v[2:3], vcc, v1, s25, v[2:3]
	v_lshl_add_u64 v[2:3], v[2:3], 0, v[56:57]
	global_load_dwordx4 v[16:19], v[2:3], off
	v_add_u32_e32 v1, s42, v0
	v_mov_b64_e32 v[2:3], s[10:11]
	v_mad_u64_u32 v[2:3], vcc, v1, s25, v[2:3]
	v_lshl_add_u64 v[2:3], v[2:3], 0, v[56:57]
	global_load_dwordx4 v[8:11], v[2:3], off
	v_add_u32_e32 v2, s43, v0
	v_mov_b64_e32 v[0:1], s[10:11]
	v_mad_u64_u32 v[0:1], vcc, v2, s25, v[0:1]
	v_lshl_add_u64 v[0:1], v[0:1], 0, v[56:57]
	global_load_dwordx4 v[20:23], v[0:1], off
	v_or_b32_e32 v2, s39, v42
	v_mov_b64_e32 v[0:1], s[10:11]
	v_mad_u64_u32 v[0:1], s[22:23], v2, s25, v[0:1]
	v_lshl_add_u64 v[0:1], v[0:1], 0, v[56:57]
	global_load_dwordx4 v[4:7], v[0:1], off
	v_add_u32_e32 v108, 0x200, v41
	v_add_u32_e32 v0, 0, v219
	v_lshrrev_b32_e32 v110, 10, v108
	v_and_b32_e32 v109, 63, v0
	v_lshl_add_u32 v1, v110, 9, v36
	v_add_u32_e32 v0, s86, v109
	v_lshlrev_b32_e32 v56, 1, v1
	v_add_u32_e32 v1, s41, v0
	v_mov_b64_e32 v[2:3], s[10:11]
	v_mad_u64_u32 v[2:3], vcc, v1, s25, v[2:3]
	v_lshl_add_u64 v[2:3], v[2:3], 0, v[56:57]
	global_load_dwordx4 v[100:103], v[2:3], off
	v_add_u32_e32 v1, s42, v0
	v_mov_b64_e32 v[2:3], s[10:11]
	v_mad_u64_u32 v[2:3], vcc, v1, s25, v[2:3]
	v_lshl_add_u64 v[2:3], v[2:3], 0, v[56:57]
	global_load_dwordx4 v[92:95], v[2:3], off
	v_add_u32_e32 v2, s43, v0
	v_mov_b64_e32 v[0:1], s[10:11]
	v_mad_u64_u32 v[0:1], vcc, v2, s25, v[0:1]
	v_lshl_add_u64 v[0:1], v[0:1], 0, v[56:57]
	global_load_dwordx4 v[104:107], v[0:1], off
	v_or_b32_e32 v2, s39, v109
	v_mov_b64_e32 v[0:1], s[10:11]
	v_mad_u64_u32 v[0:1], s[22:23], v2, s25, v[0:1]
	v_lshl_add_u64 v[0:1], v[0:1], 0, v[56:57]
	global_load_dwordx4 v[88:91], v[0:1], off
	v_lshl_add_u32 v0, v43, 11, v150
	ds_read_b128 v[44:47], v0
	ds_read_b128 v[28:31], v0 offset:16
	ds_read_b128 v[72:75], v0 offset:512
	ds_read_b128 v[24:27], v0 offset:528
	ds_read_b128 v[76:79], v0 offset:1024
	ds_read_b128 v[12:15], v0 offset:1040
	ds_read_b128 v[80:83], v0 offset:1536
	ds_read_b128 v[0:3], v0 offset:1552
	s_waitcnt vmcnt(7)
	v_lshlrev_b32_e32 v32, 16, v16
	v_and_b32_e32 v33, 0xffff0000, v16
	s_waitcnt lgkmcnt(0)
	v_pk_fma_f32 v[32:33], v[44:45], v[32:33], 0 op_sel_hi:[1,1,0]
	s_waitcnt vmcnt(6)
	v_lshlrev_b32_e32 v34, 16, v8
	v_and_b32_e32 v35, 0xffff0000, v8
	v_pk_fma_f32 v[32:33], v[72:73], v[34:35], v[32:33]
	s_waitcnt vmcnt(5)
	v_lshlrev_b32_e32 v34, 16, v20
	v_and_b32_e32 v35, 0xffff0000, v20
	v_pk_fma_f32 v[32:33], v[76:77], v[34:35], v[32:33]
	v_lshlrev_b32_e32 v16, 16, v17
	v_and_b32_e32 v17, 0xffff0000, v17
	v_pk_fma_f32 v[16:17], v[46:47], v[16:17], 0 op_sel_hi:[1,1,0]
	v_lshlrev_b32_e32 v20, 16, v18
	v_cmp_ne_u32_e32 vcc, 2, v43
	s_waitcnt vmcnt(4)
	v_lshlrev_b32_e32 v34, 16, v4
	v_and_b32_e32 v35, 0xffff0000, v4
	v_pk_fma_f32 v[32:33], v[80:81], v[34:35], v[32:33]
	s_nop 0
	v_mul_f32_e32 v4, 0xbfb8aa3b, v32
	v_exp_f32_e32 v8, v4
	v_mov_b32_e32 v4, 1.0
	v_add_f32_e32 v8, 1.0, v8
	v_rcp_f32_e32 v34, v8
	v_mul_f32_e32 v8, 0xbfb8aa3b, v33
	v_exp_f32_e32 v8, v8
	s_nop 0
	v_add_f32_e32 v8, 1.0, v8
	v_rcp_f32_e32 v35, v8
	v_lshlrev_b32_e32 v8, 16, v9
	v_and_b32_e32 v9, 0xffff0000, v9
	v_pk_fma_f32 v[8:9], v[74:75], v[8:9], v[16:17]
	v_lshlrev_b32_e32 v16, 16, v21
	v_and_b32_e32 v17, 0xffff0000, v21
	v_pk_fma_f32 v[8:9], v[78:79], v[16:17], v[8:9]
	v_lshlrev_b32_e32 v16, 16, v5
	v_and_b32_e32 v17, 0xffff0000, v5
	v_pk_fma_f32 v[8:9], v[82:83], v[16:17], v[8:9]
	v_and_b32_e32 v21, 0xffff0000, v18
	v_mul_f32_e32 v5, 0xbfb8aa3b, v8
	v_exp_f32_e32 v5, v5
	v_pk_fma_f32 v[20:21], v[28:29], v[20:21], 0 op_sel_hi:[1,1,0]
	v_lshlrev_b32_e32 v28, 16, v10
	v_and_b32_e32 v29, 0xffff0000, v10
	v_add_f32_e32 v5, 1.0, v5
	v_rcp_f32_e32 v16, v5
	v_mul_f32_e32 v5, 0xbfb8aa3b, v9
	v_exp_f32_e32 v5, v5
	v_pk_fma_f32 v[20:21], v[24:25], v[28:29], v[20:21]
	v_lshlrev_b32_e32 v24, 16, v22
	v_and_b32_e32 v25, 0xffff0000, v22
	v_pk_fma_f32 v[12:13], v[12:13], v[24:25], v[20:21]
	v_lshlrev_b32_e32 v20, 16, v6
	v_and_b32_e32 v21, 0xffff0000, v6
	v_add_f32_e32 v5, 1.0, v5
	v_pk_fma_f32 v[0:1], v[0:1], v[20:21], v[12:13]
	v_rcp_f32_e32 v17, v5
	v_mul_f32_e32 v5, 0xbfb8aa3b, v0
	v_exp_f32_e32 v5, v5
	v_lshlrev_b32_e32 v18, 16, v19
	v_and_b32_e32 v19, 0xffff0000, v19
	v_pk_fma_f32 v[18:19], v[30:31], v[18:19], 0 op_sel_hi:[1,1,0]
	v_add_f32_e32 v5, 1.0, v5
	v_rcp_f32_e32 v12, v5
	v_mul_f32_e32 v5, 0xbfb8aa3b, v1
	v_exp_f32_e32 v5, v5
	v_lshlrev_b32_e32 v10, 16, v11
	v_and_b32_e32 v11, 0xffff0000, v11
	v_pk_fma_f32 v[10:11], v[26:27], v[10:11], v[18:19]
	v_lshlrev_b32_e32 v18, 16, v23
	v_and_b32_e32 v19, 0xffff0000, v23
	v_pk_fma_f32 v[10:11], v[14:15], v[18:19], v[10:11]
	v_lshlrev_b32_e32 v6, 16, v7
	v_and_b32_e32 v7, 0xffff0000, v7
	v_add_f32_e32 v5, 1.0, v5
	v_pk_fma_f32 v[2:3], v[2:3], v[6:7], v[10:11]
	v_rcp_f32_e32 v13, v5
	v_mul_f32_e32 v5, 0xbfb8aa3b, v2
	v_exp_f32_e32 v5, v5
	v_pk_mul_f32 v[32:33], v[32:33], v[34:35]
	v_pk_mul_f32 v[8:9], v[8:9], v[16:17]
	v_pk_mul_f32 v[34:35], v[32:33], v[32:33]
	v_add_f32_e32 v5, 1.0, v5
	v_rcp_f32_e32 v6, v5
	v_mul_f32_e32 v5, 0xbfb8aa3b, v3
	v_exp_f32_e32 v5, v5
	v_pk_mul_f32 v[16:17], v[8:9], v[8:9]
	v_pk_mul_f32 v[0:1], v[0:1], v[12:13]
	v_add_f32_e32 v5, 1.0, v5
	v_rcp_f32_e32 v7, v5
	v_add_f32_e32 v5, v34, v35
	v_add_f32_e32 v5, v16, v5
	v_pk_mul_f32 v[12:13], v[0:1], v[0:1]
	v_add_f32_e32 v5, v17, v5
	v_pk_mul_f32 v[2:3], v[2:3], v[6:7]
	v_add_f32_e32 v5, v12, v5
	v_pk_mul_f32 v[6:7], v[2:3], v[2:3]
	v_add_f32_e32 v5, v13, v5
	v_add_f32_e32 v5, v6, v5
	v_add_f32_e32 v5, v7, v5
	s_nop 1
	v_add_f32_dpp v5, v5, v5 quad_perm:[1,0,3,2] row_mask:0xf bank_mask:0xf
	s_nop 1
	v_add_f32_dpp v5, v5, v5 quad_perm:[2,3,0,1] row_mask:0xf bank_mask:0xf
	s_nop 1
	v_add_f32_dpp v5, v5, v5 row_half_mirror row_mask:0xf bank_mask:0xf
	s_nop 1
	v_mov_b32_dpp v6, v5 row_mirror row_mask:0xf bank_mask:0xf
	s_and_saveexec_b64 s[22:23], vcc
	s_cbranch_execz .Ls1f0_754
; #define LAS __attribute__((address_space(3)))
; __device__ __forceinline__ float lo_bf(unsigned w) { return __uint_as_float(w << 16); }
; __device__ __forceinline__ float hi_bf(unsigned w) { return __uint_as_float(w & 0xffff0000u); }
; __device__ __forceinline__ unsigned pk2(float lo, float hi) { const f32x2_t v = {lo, hi}; const bf16x2_t b = __builtin_convertvector(v, bf16x2_t); return __builtin_bit_cast(unsigned, b); }
; __device__ __forceinline__ float silu_(float x) { return x * sigm(x); }
; __device__ __forceinline__ void dn_prep_item(const Args& a, LAS unsigned char* lds, int item, int tid, int wave, int lane, int& cwh, int next_item) {
;     ...
;     for (int r = 0; r < 6; ++r) { const int task = tid + NTHR * r, which = task >> 10, i = (task & 1023) >> 4, gq = task & 15;
;         const int col = 1024 + which * 512 + h * 128 + 8 * gq;
;         v4u xv[4];
; #pragma unroll
;         for (int jj = 0; jj < 4; ++jj) { const int pos = n * 64 + i - 3 + jj; xv[jj] = (v4u){0u, 0u, 0u, 0u};
;             if (pos >= 0) xv[jj] = *(const v4u*)(P + (size_t)(b * T + pos) * NIN + col); }
;         float o[8];
; #pragma unroll
;         for (int q = 0; q < 8; ++q) o[q] = 0.f;
; #pragma unroll
;         for (int jj = 0; jj < 4; ++jj) { const v4u v = xv[jj];
;             const f32x4 w0 = *(const LAS f32x4*)(cwl + (which * 4 + jj) * 128 + 8 * gq), w1 = *(const LAS f32x4*)(cwl + (which * 4 + jj) * 128 + 8 * gq + 4);
;             o[0] += w0[0] * lo_bf(v.x); o[1] += w0[1] * hi_bf(v.x); o[2] += w0[2] * lo_bf(v.y); o[3] += w0[3] * hi_bf(v.y);
;             o[4] += w1[0] * lo_bf(v.z); o[5] += w1[1] * hi_bf(v.z); o[6] += w1[2] * lo_bf(v.w); o[7] += w1[3] * hi_bf(v.w); }
;         float s = 0.f;
; #pragma unroll
;         for (int q = 0; q < 8; ++q) { o[q] = silu_(o[q]); s += o[q] * o[q]; }
;         s += __shfl_xor(s, 1); s += __shfl_xor(s, 2); s += __shfl_xor(s, 4); s += __shfl_xor(s, 8);
;         const float inv = which == 2 ? 1.0f : rsqrtf(s + EPS) * (which == 0 ? 0.08838834764831845f : 1.0f);
;         v4u w; w.x = pk2(o[0] * inv, o[1] * inv); w.y = pk2(o[2] * inv, o[3] * inv); w.z = pk2(o[4] * inv, o[5] * inv); w.w = pk2(o[6] * inv, o[7] * inv);
;         *(LAS v4u*)(lds + (which == 0 ? L_QS : which == 1 ? L_KH : L_V) + i * KS_ + 16 * gq) = w;
	s_waitcnt lgkmcnt(0)
	v_add_f32_e32 v4, v5, v6
	v_add_f32_e32 v4, 0x358637bd, v4
	v_mul_f32_e32 v5, 0x4b800000, v4
	v_cmp_gt_f32_e32 vcc, s34, v4
	s_nop 1
	v_cndmask_b32_e32 v4, v4, v5, vcc
	v_rsq_f32_e32 v4, v4
	s_nop 0
	v_mul_f32_e32 v5, 0x45800000, v4
	v_cndmask_b32_e32 v4, v4, v5, vcc
	v_cmp_gt_u32_e32 vcc, s30, v41
	s_nop 1
	v_cndmask_b32_e32 v5, 1.0, v231, vcc
	v_mul_f32_e32 v4, v5, v4
.Ls1f0_754:
	s_or_b64 exec, exec, s[22:23]
	v_pk_mul_f32 v[0:1], v[0:1], v[4:5] op_sel_hi:[1,0]
	v_cmp_eq_u32_e32 vcc, 1, v43
	v_cvt_pk_bf16_f32 v12, v0, v1
	v_pk_mul_f32 v[0:1], v[2:3], v[4:5] op_sel_hi:[1,0]
	s_waitcnt lgkmcnt(0)
	v_pk_mul_f32 v[6:7], v[32:33], v[4:5] op_sel_hi:[1,0]
	v_cvt_pk_bf16_f32 v13, v0, v1
	v_cndmask_b32_e64 v0, v188, 0, vcc
	v_cmp_lt_u32_e32 vcc, s31, v41
	v_cvt_pk_bf16_f32 v10, v6, v7
	v_pk_mul_f32 v[6:7], v[8:9], v[4:5] op_sel_hi:[1,0]
	v_cndmask_b32_e32 v0, v232, v0, vcc
	v_add_u32_e32 v0, 0, v0
	v_mul_u32_u24_e32 v1, 0x110, v42
	v_cvt_pk_bf16_f32 v11, v6, v7
	v_add3_u32 v0, v0, v1, v151
	ds_write_b128 v0, v[10:13]
	v_add_u32_e32 v0, 0x400, v41
	v_lshrrev_b32_e32 v43, 10, v0
	v_add_u32_e32 v0, 0, v218
	v_and_b32_e32 v42, 63, v0
	v_lshl_add_u32 v1, v43, 9, v36
	v_add_u32_e32 v0, s86, v42
	v_lshlrev_b32_e32 v56, 1, v1
	v_add_u32_e32 v1, s41, v0
	v_mov_b64_e32 v[2:3], s[10:11]
	v_mad_u64_u32 v[2:3], vcc, v1, s25, v[2:3]
	v_lshl_add_u64 v[2:3], v[2:3], 0, v[56:57]
	global_load_dwordx4 v[16:19], v[2:3], off
	v_add_u32_e32 v1, s42, v0
	v_mov_b64_e32 v[2:3], s[10:11]
	v_mad_u64_u32 v[2:3], vcc, v1, s25, v[2:3]
	v_lshl_add_u64 v[2:3], v[2:3], 0, v[56:57]
	global_load_dwordx4 v[8:11], v[2:3], off
	v_add_u32_e32 v2, s43, v0
	v_mov_b64_e32 v[0:1], s[10:11]
	v_mad_u64_u32 v[0:1], vcc, v2, s25, v[0:1]
	v_lshl_add_u64 v[0:1], v[0:1], 0, v[56:57]
	global_load_dwordx4 v[20:23], v[0:1], off
	v_or_b32_e32 v2, s39, v42
	v_mov_b64_e32 v[0:1], s[10:11]
	v_mad_u64_u32 v[0:1], s[22:23], v2, s25, v[0:1]
	v_lshl_add_u64 v[0:1], v[0:1], 0, v[56:57]
	global_load_dwordx4 v[4:7], v[0:1], off
	v_lshl_add_u32 v0, v110, 11, v150
	ds_read_b128 v[72:75], v0
	ds_read_b128 v[28:31], v0 offset:16
	ds_read_b128 v[76:79], v0 offset:512
	ds_read_b128 v[24:27], v0 offset:528
	ds_read_b128 v[80:83], v0 offset:1024
	ds_read_b128 v[96:99], v0 offset:1040
	ds_read_b128 v[84:87], v0 offset:1536
	ds_read_b128 v[0:3], v0 offset:1552
	s_waitcnt vmcnt(7)
	v_lshlrev_b32_e32 v32, 16, v100
	v_and_b32_e32 v33, 0xffff0000, v100
	s_waitcnt lgkmcnt(7)
	v_pk_fma_f32 v[32:33], v[72:73], v[32:33], 0 op_sel_hi:[1,1,0]
	s_waitcnt vmcnt(6)
	v_lshlrev_b32_e32 v34, 16, v92
	v_and_b32_e32 v35, 0xffff0000, v92
	s_waitcnt lgkmcnt(5)
	v_pk_fma_f32 v[32:33], v[76:77], v[34:35], v[32:33]
	s_waitcnt vmcnt(5)
	v_lshlrev_b32_e32 v34, 16, v104
	v_and_b32_e32 v35, 0xffff0000, v104
	s_waitcnt lgkmcnt(3)
	v_pk_fma_f32 v[32:33], v[80:81], v[34:35], v[32:33]
	v_lshlrev_b32_e32 v100, 16, v101
	v_and_b32_e32 v101, 0xffff0000, v101
	v_pk_fma_f32 v[100:101], v[74:75], v[100:101], 0 op_sel_hi:[1,1,0]
	v_lshlrev_b32_e32 v104, 16, v102
	v_cmp_ne_u32_e32 vcc, 2, v110
	s_waitcnt vmcnt(4)
	v_lshlrev_b32_e32 v34, 16, v88
	v_and_b32_e32 v35, 0xffff0000, v88
	s_waitcnt lgkmcnt(1)
	v_pk_fma_f32 v[32:33], v[84:85], v[34:35], v[32:33]
	s_nop 0
	v_mul_f32_e32 v88, 0xbfb8aa3b, v32
	v_exp_f32_e32 v92, v88
	v_mov_b32_e32 v88, 1.0
	v_add_f32_e32 v92, 1.0, v92
	v_rcp_f32_e32 v34, v92
	v_mul_f32_e32 v92, 0xbfb8aa3b, v33
	v_exp_f32_e32 v92, v92
	s_nop 0
	v_add_f32_e32 v92, 1.0, v92
	v_rcp_f32_e32 v35, v92
	v_lshlrev_b32_e32 v92, 16, v93
	v_and_b32_e32 v93, 0xffff0000, v93
	v_pk_fma_f32 v[92:93], v[78:79], v[92:93], v[100:101]
	v_lshlrev_b32_e32 v100, 16, v105
	v_and_b32_e32 v101, 0xffff0000, v105
	v_pk_fma_f32 v[92:93], v[82:83], v[100:101], v[92:93]
	v_lshlrev_b32_e32 v100, 16, v89
	v_and_b32_e32 v101, 0xffff0000, v89
	v_pk_fma_f32 v[92:93], v[86:87], v[100:101], v[92:93]
	v_and_b32_e32 v105, 0xffff0000, v102
	v_mul_f32_e32 v89, 0xbfb8aa3b, v92
	v_exp_f32_e32 v89, v89
	v_pk_fma_f32 v[104:105], v[28:29], v[104:105], 0 op_sel_hi:[1,1,0]
	v_lshlrev_b32_e32 v28, 16, v94
	v_and_b32_e32 v29, 0xffff0000, v94
	v_add_f32_e32 v89, 1.0, v89
	v_rcp_f32_e32 v100, v89
	v_mul_f32_e32 v89, 0xbfb8aa3b, v93
	v_exp_f32_e32 v89, v89
	v_pk_fma_f32 v[104:105], v[24:25], v[28:29], v[104:105]
	v_lshlrev_b32_e32 v24, 16, v106
	v_and_b32_e32 v25, 0xffff0000, v106
	v_pk_fma_f32 v[96:97], v[96:97], v[24:25], v[104:105]
	v_lshlrev_b32_e32 v104, 16, v90
	v_and_b32_e32 v105, 0xffff0000, v90
	v_add_f32_e32 v89, 1.0, v89
	s_waitcnt lgkmcnt(0)
	v_pk_fma_f32 v[0:1], v[0:1], v[104:105], v[96:97]
	v_rcp_f32_e32 v101, v89
	v_mul_f32_e32 v89, 0xbfb8aa3b, v0
	v_exp_f32_e32 v89, v89
	v_lshlrev_b32_e32 v102, 16, v103
	v_and_b32_e32 v103, 0xffff0000, v103
	v_pk_fma_f32 v[102:103], v[30:31], v[102:103], 0 op_sel_hi:[1,1,0]
	v_add_f32_e32 v89, 1.0, v89
	v_rcp_f32_e32 v96, v89
	v_mul_f32_e32 v89, 0xbfb8aa3b, v1
	v_exp_f32_e32 v89, v89
	v_lshlrev_b32_e32 v94, 16, v95
	v_and_b32_e32 v95, 0xffff0000, v95
	v_pk_fma_f32 v[94:95], v[26:27], v[94:95], v[102:103]
	v_lshlrev_b32_e32 v102, 16, v107
	v_and_b32_e32 v103, 0xffff0000, v107
	v_pk_fma_f32 v[94:95], v[98:99], v[102:103], v[94:95]
	v_lshlrev_b32_e32 v90, 16, v91
	v_and_b32_e32 v91, 0xffff0000, v91
	v_add_f32_e32 v89, 1.0, v89
	v_pk_fma_f32 v[2:3], v[2:3], v[90:91], v[94:95]
	v_rcp_f32_e32 v97, v89
	v_mul_f32_e32 v89, 0xbfb8aa3b, v2
	v_exp_f32_e32 v89, v89
	v_pk_mul_f32 v[32:33], v[32:33], v[34:35]
	v_pk_mul_f32 v[92:93], v[92:93], v[100:101]
	v_pk_mul_f32 v[34:35], v[32:33], v[32:33]
	v_add_f32_e32 v89, 1.0, v89
	v_rcp_f32_e32 v90, v89
	v_mul_f32_e32 v89, 0xbfb8aa3b, v3
	v_exp_f32_e32 v89, v89
	v_pk_mul_f32 v[100:101], v[92:93], v[92:93]
	v_pk_mul_f32 v[0:1], v[0:1], v[96:97]
	v_add_f32_e32 v89, 1.0, v89
	v_rcp_f32_e32 v91, v89
	v_add_f32_e32 v89, v34, v35
	v_add_f32_e32 v89, v100, v89
	v_pk_mul_f32 v[96:97], v[0:1], v[0:1]
	v_add_f32_e32 v89, v101, v89
	v_pk_mul_f32 v[2:3], v[2:3], v[90:91]
	v_add_f32_e32 v89, v96, v89
	v_pk_mul_f32 v[90:91], v[2:3], v[2:3]
	v_add_f32_e32 v89, v97, v89
	v_add_f32_e32 v89, v90, v89
	v_add_f32_e32 v89, v91, v89
	s_nop 1
	v_add_f32_dpp v89, v89, v89 quad_perm:[1,0,3,2] row_mask:0xf bank_mask:0xf
	s_nop 1
	v_add_f32_dpp v89, v89, v89 quad_perm:[2,3,0,1] row_mask:0xf bank_mask:0xf
	s_nop 1
	v_add_f32_dpp v89, v89, v89 row_half_mirror row_mask:0xf bank_mask:0xf
	s_nop 1
	v_mov_b32_dpp v90, v89 row_mirror row_mask:0xf bank_mask:0xf
	s_and_saveexec_b64 s[22:23], vcc
	s_cbranch_execz .Ls1f1_762
	s_waitcnt lgkmcnt(0)
	v_add_f32_e32 v88, v89, v90
	v_add_f32_e32 v88, 0x358637bd, v88
	v_mul_f32_e32 v89, 0x4b800000, v88
	v_cmp_gt_f32_e32 vcc, s34, v88
	s_nop 1
	v_cndmask_b32_e32 v88, v88, v89, vcc
	v_rsq_f32_e32 v88, v88
	s_nop 0
	v_mul_f32_e32 v89, 0x45800000, v88
	v_cndmask_b32_e32 v88, v88, v89, vcc
	v_cmp_gt_u32_e32 vcc, s30, v108
	s_nop 1
	v_cndmask_b32_e32 v89, 1.0, v231, vcc
	v_mul_f32_e32 v88, v89, v88
; #define LAS __attribute__((address_space(3)))
; __device__ __forceinline__ float lo_bf(unsigned w) { return __uint_as_float(w << 16); }
; __device__ __forceinline__ float hi_bf(unsigned w) { return __uint_as_float(w & 0xffff0000u); }
; __device__ __forceinline__ unsigned pk2(float lo, float hi) { const f32x2_t v = {lo, hi}; const bf16x2_t b = __builtin_convertvector(v, bf16x2_t); return __builtin_bit_cast(unsigned, b); }
; __device__ __forceinline__ float silu_(float x) { return x * sigm(x); }
; __device__ __forceinline__ void dn_prep_item(const Args& a, LAS unsigned char* lds, int item, int tid, int wave, int lane, int& cwh, int next_item) {
;     ...
;     for (int r = 0; r < 6; ++r) { const int task = tid + NTHR * r, which = task >> 10, i = (task & 1023) >> 4, gq = task & 15;
;         const int col = 1024 + which * 512 + h * 128 + 8 * gq;
;         v4u xv[4];
; #pragma unroll
;         for (int jj = 0; jj < 4; ++jj) { const int pos = n * 64 + i - 3 + jj; xv[jj] = (v4u){0u, 0u, 0u, 0u};
;             if (pos >= 0) xv[jj] = *(const v4u*)(P + (size_t)(b * T + pos) * NIN + col); }
;         float o[8];
; #pragma unroll
;         for (int q = 0; q < 8; ++q) o[q] = 0.f;
; #pragma unroll
;         for (int jj = 0; jj < 4; ++jj) { const v4u v = xv[jj];
;             const f32x4 w0 = *(const LAS f32x4*)(cwl + (which * 4 + jj) * 128 + 8 * gq), w1 = *(const LAS f32x4*)(cwl + (which * 4 + jj) * 128 + 8 * gq + 4);
;             o[0] += w0[0] * lo_bf(v.x); o[1] += w0[1] * hi_bf(v.x); o[2] += w0[2] * lo_bf(v.y); o[3] += w0[3] * hi_bf(v.y);
;             o[4] += w1[0] * lo_bf(v.z); o[5] += w1[1] * hi_bf(v.z); o[6] += w1[2] * lo_bf(v.w); o[7] += w1[3] * hi_bf(v.w); }
;         float s = 0.f;
; #pragma unroll
;         for (int q = 0; q < 8; ++q) { o[q] = silu_(o[q]); s += o[q] * o[q]; }
;         s += __shfl_xor(s, 1); s += __shfl_xor(s, 2); s += __shfl_xor(s, 4); s += __shfl_xor(s, 8);
;         const float inv = which == 2 ? 1.0f : rsqrtf(s + EPS) * (which == 0 ? 0.08838834764831845f : 1.0f);
;         v4u w; w.x = pk2(o[0] * inv, o[1] * inv); w.y = pk2(o[2] * inv, o[3] * inv); w.z = pk2(o[4] * inv, o[5] * inv); w.w = pk2(o[6] * inv, o[7] * inv);
;         *(LAS v4u*)(lds + (which == 0 ? L_QS : which == 1 ? L_KH : L_V) + i * KS_ + 16 * gq) = w;
.Ls1f1_762:
	s_or_b64 exec, exec, s[22:23]
	v_pk_mul_f32 v[0:1], v[0:1], v[88:89] op_sel_hi:[1,0]
	v_cmp_eq_u32_e32 vcc, 1, v110
	v_cvt_pk_bf16_f32 v96, v0, v1
	v_pk_mul_f32 v[0:1], v[2:3], v[88:89] op_sel_hi:[1,0]
	s_waitcnt lgkmcnt(0)
	v_pk_mul_f32 v[90:91], v[32:33], v[88:89] op_sel_hi:[1,0]
	v_cvt_pk_bf16_f32 v97, v0, v1
	v_cndmask_b32_e64 v0, v188, 0, vcc
	v_cmp_lt_u32_e32 vcc, s31, v108
	v_cvt_pk_bf16_f32 v94, v90, v91
	v_pk_mul_f32 v[90:91], v[92:93], v[88:89] op_sel_hi:[1,0]
	v_cndmask_b32_e32 v0, v232, v0, vcc
	v_add_u32_e32 v0, 0, v0
	v_mul_u32_u24_e32 v1, 0x110, v109
	v_cvt_pk_bf16_f32 v95, v90, v91
	v_add3_u32 v0, v0, v1, v151
	ds_write_b128 v0, v[94:97]
	v_add_u32_e32 v111, 0x600, v41
	v_add_u32_e32 v0, 0x60, v220
	v_lshrrev_b32_e32 v109, 10, v111
	v_and_b32_e32 v108, 63, v0
	v_lshl_add_u32 v1, v109, 9, v36
	v_add_u32_e32 v0, s86, v108
	v_lshlrev_b32_e32 v56, 1, v1
	v_add_u32_e32 v1, s41, v0
	v_mov_b64_e32 v[2:3], s[10:11]
	v_mad_u64_u32 v[2:3], vcc, v1, s25, v[2:3]
	v_lshl_add_u64 v[2:3], v[2:3], 0, v[56:57]
	global_load_dwordx4 v[100:103], v[2:3], off
	v_add_u32_e32 v1, s42, v0
	v_mov_b64_e32 v[2:3], s[10:11]
	v_mad_u64_u32 v[2:3], vcc, v1, s25, v[2:3]
	v_lshl_add_u64 v[2:3], v[2:3], 0, v[56:57]
	global_load_dwordx4 v[92:95], v[2:3], off
	v_add_u32_e32 v2, s43, v0
	v_mov_b64_e32 v[0:1], s[10:11]
	v_mad_u64_u32 v[0:1], vcc, v2, s25, v[0:1]
	v_lshl_add_u64 v[0:1], v[0:1], 0, v[56:57]
	global_load_dwordx4 v[104:107], v[0:1], off
	v_or_b32_e32 v2, s39, v108
	v_mov_b64_e32 v[0:1], s[10:11]
	v_mad_u64_u32 v[0:1], s[22:23], v2, s25, v[0:1]
	v_lshl_add_u64 v[0:1], v[0:1], 0, v[56:57]
	global_load_dwordx4 v[88:91], v[0:1], off
	v_lshl_add_u32 v0, v43, 11, v150
	ds_read_b128 v[44:47], v0
	ds_read_b128 v[28:31], v0 offset:16
	ds_read_b128 v[72:75], v0 offset:512
	ds_read_b128 v[24:27], v0 offset:528
	ds_read_b128 v[76:79], v0 offset:1024
	ds_read_b128 v[12:15], v0 offset:1040
	ds_read_b128 v[80:83], v0 offset:1536
	ds_read_b128 v[0:3], v0 offset:1552
	s_waitcnt vmcnt(7)
	v_lshlrev_b32_e32 v32, 16, v16
	v_and_b32_e32 v33, 0xffff0000, v16
	s_waitcnt lgkmcnt(7)
	v_pk_fma_f32 v[32:33], v[44:45], v[32:33], 0 op_sel_hi:[1,1,0]
	s_waitcnt vmcnt(6)
	v_lshlrev_b32_e32 v34, 16, v8
	v_and_b32_e32 v35, 0xffff0000, v8
	s_waitcnt lgkmcnt(5)
	v_pk_fma_f32 v[32:33], v[72:73], v[34:35], v[32:33]
	s_waitcnt vmcnt(5)
	v_lshlrev_b32_e32 v34, 16, v20
	v_and_b32_e32 v35, 0xffff0000, v20
	s_waitcnt lgkmcnt(3)
	v_pk_fma_f32 v[32:33], v[76:77], v[34:35], v[32:33]
	v_lshlrev_b32_e32 v16, 16, v17
	v_and_b32_e32 v17, 0xffff0000, v17
	v_pk_fma_f32 v[16:17], v[46:47], v[16:17], 0 op_sel_hi:[1,1,0]
	v_lshlrev_b32_e32 v20, 16, v18
	v_cmp_ne_u32_e32 vcc, 2, v43
	s_waitcnt vmcnt(4)
	v_lshlrev_b32_e32 v34, 16, v4
	v_and_b32_e32 v35, 0xffff0000, v4
	s_waitcnt lgkmcnt(1)
	v_pk_fma_f32 v[32:33], v[80:81], v[34:35], v[32:33]
	s_nop 0
	v_mul_f32_e32 v4, 0xbfb8aa3b, v32
	v_exp_f32_e32 v8, v4
	v_mov_b32_e32 v4, 1.0
	v_add_f32_e32 v8, 1.0, v8
	v_rcp_f32_e32 v34, v8
	v_mul_f32_e32 v8, 0xbfb8aa3b, v33
	v_exp_f32_e32 v8, v8
	s_nop 0
	v_add_f32_e32 v8, 1.0, v8
	v_rcp_f32_e32 v35, v8
	v_lshlrev_b32_e32 v8, 16, v9
	v_and_b32_e32 v9, 0xffff0000, v9
	v_pk_fma_f32 v[8:9], v[74:75], v[8:9], v[16:17]
	v_lshlrev_b32_e32 v16, 16, v21
	v_and_b32_e32 v17, 0xffff0000, v21
	v_pk_fma_f32 v[8:9], v[78:79], v[16:17], v[8:9]
	v_lshlrev_b32_e32 v16, 16, v5
	v_and_b32_e32 v17, 0xffff0000, v5
	v_pk_fma_f32 v[8:9], v[82:83], v[16:17], v[8:9]
	v_and_b32_e32 v21, 0xffff0000, v18
	v_mul_f32_e32 v5, 0xbfb8aa3b, v8
	v_exp_f32_e32 v5, v5
	v_pk_fma_f32 v[20:21], v[28:29], v[20:21], 0 op_sel_hi:[1,1,0]
	v_lshlrev_b32_e32 v28, 16, v10
	v_and_b32_e32 v29, 0xffff0000, v10
	v_add_f32_e32 v5, 1.0, v5
	v_rcp_f32_e32 v16, v5
	v_mul_f32_e32 v5, 0xbfb8aa3b, v9
	v_exp_f32_e32 v5, v5
	v_pk_fma_f32 v[20:21], v[24:25], v[28:29], v[20:21]
	v_lshlrev_b32_e32 v24, 16, v22
	v_and_b32_e32 v25, 0xffff0000, v22
	v_pk_fma_f32 v[12:13], v[12:13], v[24:25], v[20:21]
	v_lshlrev_b32_e32 v20, 16, v6
	v_and_b32_e32 v21, 0xffff0000, v6
	v_add_f32_e32 v5, 1.0, v5
	s_waitcnt lgkmcnt(0)
	v_pk_fma_f32 v[0:1], v[0:1], v[20:21], v[12:13]
	v_rcp_f32_e32 v17, v5
	v_mul_f32_e32 v5, 0xbfb8aa3b, v0
	v_exp_f32_e32 v5, v5
	v_lshlrev_b32_e32 v18, 16, v19
	v_and_b32_e32 v19, 0xffff0000, v19
	v_pk_fma_f32 v[18:19], v[30:31], v[18:19], 0 op_sel_hi:[1,1,0]
	v_add_f32_e32 v5, 1.0, v5
	v_rcp_f32_e32 v12, v5
	v_mul_f32_e32 v5, 0xbfb8aa3b, v1
	v_exp_f32_e32 v5, v5
	v_lshlrev_b32_e32 v10, 16, v11
	v_and_b32_e32 v11, 0xffff0000, v11
	v_pk_fma_f32 v[10:11], v[26:27], v[10:11], v[18:19]
	v_lshlrev_b32_e32 v18, 16, v23
	v_and_b32_e32 v19, 0xffff0000, v23
	v_pk_fma_f32 v[10:11], v[14:15], v[18:19], v[10:11]
	v_lshlrev_b32_e32 v6, 16, v7
	v_and_b32_e32 v7, 0xffff0000, v7
	v_add_f32_e32 v5, 1.0, v5
	v_pk_fma_f32 v[2:3], v[2:3], v[6:7], v[10:11]
	v_rcp_f32_e32 v13, v5
	v_mul_f32_e32 v5, 0xbfb8aa3b, v2
	v_exp_f32_e32 v5, v5
	v_pk_mul_f32 v[32:33], v[32:33], v[34:35]
	v_pk_mul_f32 v[8:9], v[8:9], v[16:17]
	v_pk_mul_f32 v[34:35], v[32:33], v[32:33]
	v_add_f32_e32 v5, 1.0, v5
	v_rcp_f32_e32 v6, v5
	v_mul_f32_e32 v5, 0xbfb8aa3b, v3
	v_exp_f32_e32 v5, v5
	v_pk_mul_f32 v[16:17], v[8:9], v[8:9]
	v_pk_mul_f32 v[0:1], v[0:1], v[12:13]
	v_add_f32_e32 v5, 1.0, v5
	v_rcp_f32_e32 v7, v5
	v_add_f32_e32 v5, v34, v35
	v_add_f32_e32 v5, v16, v5
	v_pk_mul_f32 v[12:13], v[0:1], v[0:1]
	v_add_f32_e32 v5, v17, v5
	v_pk_mul_f32 v[2:3], v[2:3], v[6:7]
	v_add_f32_e32 v5, v12, v5
	v_pk_mul_f32 v[6:7], v[2:3], v[2:3]
	v_add_f32_e32 v5, v13, v5
	v_add_f32_e32 v5, v6, v5
	v_add_f32_e32 v5, v7, v5
	s_nop 1
	v_add_f32_dpp v5, v5, v5 quad_perm:[1,0,3,2] row_mask:0xf bank_mask:0xf
	s_nop 1
	v_add_f32_dpp v5, v5, v5 quad_perm:[2,3,0,1] row_mask:0xf bank_mask:0xf
	s_nop 1
	v_add_f32_dpp v5, v5, v5 row_half_mirror row_mask:0xf bank_mask:0xf
	s_nop 1
	v_mov_b32_dpp v6, v5 row_mirror row_mask:0xf bank_mask:0xf
	s_and_saveexec_b64 s[22:23], vcc
	s_cbranch_execz .Ls1f2_745
	s_waitcnt lgkmcnt(0)
	v_add_f32_e32 v4, v5, v6
	v_add_f32_e32 v4, 0x358637bd, v4
	v_mul_f32_e32 v5, 0x4b800000, v4
	v_cmp_gt_f32_e32 vcc, s34, v4
	s_nop 1
	v_cndmask_b32_e32 v4, v4, v5, vcc
	v_rsq_f32_e32 v4, v4
	s_nop 0
	v_mul_f32_e32 v5, 0x45800000, v4
	v_cndmask_b32_e32 v4, v4, v5, vcc
; #define LAS __attribute__((address_space(3)))
; __device__ __forceinline__ float lo_bf(unsigned w) { return __uint_as_float(w << 16); }
; __device__ __forceinline__ float hi_bf(unsigned w) { return __uint_as_float(w & 0xffff0000u); }
; __device__ __forceinline__ unsigned pk2(float lo, float hi) { const f32x2_t v = {lo, hi}; const bf16x2_t b = __builtin_convertvector(v, bf16x2_t); return __builtin_bit_cast(unsigned, b); }
; __device__ __forceinline__ float silu_(float x) { return x * sigm(x); }
; __device__ __forceinline__ void dn_prep_item(const Args& a, LAS unsigned char* lds, int item, int tid, int wave, int lane, int& cwh, int next_item) {
;     ...
;     for (int r = 0; r < 6; ++r) { const int task = tid + NTHR * r, which = task >> 10, i = (task & 1023) >> 4, gq = task & 15;
;         const int col = 1024 + which * 512 + h * 128 + 8 * gq;
;         v4u xv[4];
; #pragma unroll
;         for (int jj = 0; jj < 4; ++jj) { const int pos = n * 64 + i - 3 + jj; xv[jj] = (v4u){0u, 0u, 0u, 0u};
;             if (pos >= 0) xv[jj] = *(const v4u*)(P + (size_t)(b * T + pos) * NIN + col); }
;         float o[8];
; #pragma unroll
;         for (int q = 0; q < 8; ++q) o[q] = 0.f;
; #pragma unroll
;         for (int jj = 0; jj < 4; ++jj) { const v4u v = xv[jj];
;             const f32x4 w0 = *(const LAS f32x4*)(cwl + (which * 4 + jj) * 128 + 8 * gq), w1 = *(const LAS f32x4*)(cwl + (which * 4 + jj) * 128 + 8 * gq + 4);
;             o[0] += w0[0] * lo_bf(v.x); o[1] += w0[1] * hi_bf(v.x); o[2] += w0[2] * lo_bf(v.y); o[3] += w0[3] * hi_bf(v.y);
;             o[4] += w1[0] * lo_bf(v.z); o[5] += w1[1] * hi_bf(v.z); o[6] += w1[2] * lo_bf(v.w); o[7] += w1[3] * hi_bf(v.w); }
;         float s = 0.f;
; #pragma unroll
;         for (int q = 0; q < 8; ++q) { o[q] = silu_(o[q]); s += o[q] * o[q]; }
;         s += __shfl_xor(s, 1); s += __shfl_xor(s, 2); s += __shfl_xor(s, 4); s += __shfl_xor(s, 8);
;         const float inv = which == 2 ? 1.0f : rsqrtf(s + EPS) * (which == 0 ? 0.08838834764831845f : 1.0f);
;         v4u w; w.x = pk2(o[0] * inv, o[1] * inv); w.y = pk2(o[2] * inv, o[3] * inv); w.z = pk2(o[4] * inv, o[5] * inv); w.w = pk2(o[6] * inv, o[7] * inv);
;         *(LAS v4u*)(lds + (which == 0 ? L_QS : which == 1 ? L_KH : L_V) + i * KS_ + 16 * gq) = w;
.Ls1f2_745:
	s_or_b64 exec, exec, s[22:23]
	s_waitcnt lgkmcnt(0)
	v_pk_mul_f32 v[6:7], v[32:33], v[4:5] op_sel_hi:[1,0]
	v_pk_mul_f32 v[8:9], v[8:9], v[4:5] op_sel_hi:[1,0]
	v_pk_mul_f32 v[0:1], v[0:1], v[4:5] op_sel_hi:[1,0]
	v_cvt_pk_bf16_f32 v6, v6, v7
	v_cvt_pk_bf16_f32 v7, v8, v9
	v_cvt_pk_bf16_f32 v8, v0, v1
	v_pk_mul_f32 v[0:1], v[2:3], v[4:5] op_sel_hi:[1,0]
	v_cmp_eq_u32_e32 vcc, 1, v43
	v_cvt_pk_bf16_f32 v9, v0, v1
	v_mul_u32_u24_e32 v1, 0x110, v42
	v_cndmask_b32_e64 v0, v188, 0, vcc
	v_add_u32_e32 v0, 0, v0
	v_add3_u32 v0, v0, v1, v151
	ds_write_b128 v0, v[6:9]
	v_add_u32_e32 v112, 0x200, v111
	v_add_u32_e32 v0, 0x60, v219
	v_lshrrev_b32_e32 v114, 10, v112
	v_and_b32_e32 v113, 63, v0
	v_lshl_add_u32 v1, v114, 9, v36
	v_add_u32_e32 v0, s86, v113
	v_lshlrev_b32_e32 v56, 1, v1
	v_add_u32_e32 v1, s41, v0
	v_mov_b64_e32 v[2:3], s[10:11]
	v_mad_u64_u32 v[2:3], vcc, v1, s25, v[2:3]
	v_lshl_add_u64 v[2:3], v[2:3], 0, v[56:57]
	global_load_dwordx4 v[16:19], v[2:3], off
	v_add_u32_e32 v1, s42, v0
	v_mov_b64_e32 v[2:3], s[10:11]
	v_mad_u64_u32 v[2:3], vcc, v1, s25, v[2:3]
	v_lshl_add_u64 v[2:3], v[2:3], 0, v[56:57]
	global_load_dwordx4 v[8:11], v[2:3], off
	v_add_u32_e32 v2, s43, v0
	v_mov_b64_e32 v[0:1], s[10:11]
	v_mad_u64_u32 v[0:1], vcc, v2, s25, v[0:1]
	v_lshl_add_u64 v[0:1], v[0:1], 0, v[56:57]
	global_load_dwordx4 v[20:23], v[0:1], off
	v_or_b32_e32 v2, s39, v113
	v_mov_b64_e32 v[0:1], s[10:11]
	v_mad_u64_u32 v[0:1], s[22:23], v2, s25, v[0:1]
	v_lshl_add_u64 v[0:1], v[0:1], 0, v[56:57]
	global_load_dwordx4 v[4:7], v[0:1], off
	v_lshl_add_u32 v0, v109, 11, v150
	ds_read_b128 v[44:47], v0
	ds_read_b128 v[28:31], v0 offset:16
	ds_read_b128 v[72:75], v0 offset:512
	ds_read_b128 v[24:27], v0 offset:528
	ds_read_b128 v[76:79], v0 offset:1024
	ds_read_b128 v[96:99], v0 offset:1040
	ds_read_b128 v[80:83], v0 offset:1536
	ds_read_b128 v[0:3], v0 offset:1552
	s_waitcnt vmcnt(7)
	v_lshlrev_b32_e32 v32, 16, v100
	v_and_b32_e32 v33, 0xffff0000, v100
	s_waitcnt lgkmcnt(0)
	v_pk_fma_f32 v[32:33], v[44:45], v[32:33], 0 op_sel_hi:[1,1,0]
	s_waitcnt vmcnt(6)
	v_lshlrev_b32_e32 v34, 16, v92
	v_and_b32_e32 v35, 0xffff0000, v92
	v_pk_fma_f32 v[32:33], v[72:73], v[34:35], v[32:33]
	s_waitcnt vmcnt(5)
	v_lshlrev_b32_e32 v34, 16, v104
	v_and_b32_e32 v35, 0xffff0000, v104
	v_pk_fma_f32 v[32:33], v[76:77], v[34:35], v[32:33]
	v_lshlrev_b32_e32 v100, 16, v101
	v_and_b32_e32 v101, 0xffff0000, v101
	v_pk_fma_f32 v[100:101], v[46:47], v[100:101], 0 op_sel_hi:[1,1,0]
	v_lshlrev_b32_e32 v104, 16, v102
	v_cmp_ne_u32_e32 vcc, 2, v109
	s_waitcnt vmcnt(4)
	v_lshlrev_b32_e32 v34, 16, v88
	v_and_b32_e32 v35, 0xffff0000, v88
	v_pk_fma_f32 v[32:33], v[80:81], v[34:35], v[32:33]
	s_nop 0
	v_mul_f32_e32 v88, 0xbfb8aa3b, v32
	v_exp_f32_e32 v92, v88
	v_mov_b32_e32 v88, 1.0
	v_add_f32_e32 v92, 1.0, v92
	v_rcp_f32_e32 v34, v92
	v_mul_f32_e32 v92, 0xbfb8aa3b, v33
	v_exp_f32_e32 v92, v92
	s_nop 0
	v_add_f32_e32 v92, 1.0, v92
	v_rcp_f32_e32 v35, v92
	v_lshlrev_b32_e32 v92, 16, v93
	v_and_b32_e32 v93, 0xffff0000, v93
	v_pk_fma_f32 v[92:93], v[74:75], v[92:93], v[100:101]
	v_lshlrev_b32_e32 v100, 16, v105
	v_and_b32_e32 v101, 0xffff0000, v105
	v_pk_fma_f32 v[92:93], v[78:79], v[100:101], v[92:93]
	v_lshlrev_b32_e32 v100, 16, v89
	v_and_b32_e32 v101, 0xffff0000, v89
	v_pk_fma_f32 v[92:93], v[82:83], v[100:101], v[92:93]
	v_and_b32_e32 v105, 0xffff0000, v102
	v_mul_f32_e32 v89, 0xbfb8aa3b, v92
	v_exp_f32_e32 v89, v89
	v_pk_fma_f32 v[104:105], v[28:29], v[104:105], 0 op_sel_hi:[1,1,0]
	v_lshlrev_b32_e32 v28, 16, v94
	v_and_b32_e32 v29, 0xffff0000, v94
	v_add_f32_e32 v89, 1.0, v89
	v_rcp_f32_e32 v100, v89
	v_mul_f32_e32 v89, 0xbfb8aa3b, v93
	v_exp_f32_e32 v89, v89
	v_pk_fma_f32 v[104:105], v[24:25], v[28:29], v[104:105]
	v_lshlrev_b32_e32 v24, 16, v106
	v_and_b32_e32 v25, 0xffff0000, v106
	v_pk_fma_f32 v[96:97], v[96:97], v[24:25], v[104:105]
	v_lshlrev_b32_e32 v104, 16, v90
	v_and_b32_e32 v105, 0xffff0000, v90
	v_add_f32_e32 v89, 1.0, v89
	v_pk_fma_f32 v[0:1], v[0:1], v[104:105], v[96:97]
	v_rcp_f32_e32 v101, v89
	v_mul_f32_e32 v89, 0xbfb8aa3b, v0
	v_exp_f32_e32 v89, v89
	v_lshlrev_b32_e32 v102, 16, v103
	v_and_b32_e32 v103, 0xffff0000, v103
	v_pk_fma_f32 v[102:103], v[30:31], v[102:103], 0 op_sel_hi:[1,1,0]
	v_add_f32_e32 v89, 1.0, v89
	v_rcp_f32_e32 v96, v89
	v_mul_f32_e32 v89, 0xbfb8aa3b, v1
	v_exp_f32_e32 v89, v89
	v_lshlrev_b32_e32 v94, 16, v95
	v_and_b32_e32 v95, 0xffff0000, v95
	v_pk_fma_f32 v[94:95], v[26:27], v[94:95], v[102:103]
	v_lshlrev_b32_e32 v102, 16, v107
	v_and_b32_e32 v103, 0xffff0000, v107
	v_pk_fma_f32 v[94:95], v[98:99], v[102:103], v[94:95]
	v_lshlrev_b32_e32 v90, 16, v91
	v_and_b32_e32 v91, 0xffff0000, v91
	v_add_f32_e32 v89, 1.0, v89
	v_pk_fma_f32 v[2:3], v[2:3], v[90:91], v[94:95]
	v_rcp_f32_e32 v97, v89
	v_mul_f32_e32 v89, 0xbfb8aa3b, v2
	v_exp_f32_e32 v89, v89
	v_pk_mul_f32 v[32:33], v[32:33], v[34:35]
	v_pk_mul_f32 v[92:93], v[92:93], v[100:101]
	v_pk_mul_f32 v[34:35], v[32:33], v[32:33]
	v_add_f32_e32 v89, 1.0, v89
	v_rcp_f32_e32 v90, v89
	v_mul_f32_e32 v89, 0xbfb8aa3b, v3
	v_exp_f32_e32 v89, v89
	v_pk_mul_f32 v[100:101], v[92:93], v[92:93]
	v_pk_mul_f32 v[0:1], v[0:1], v[96:97]
	v_add_f32_e32 v89, 1.0, v89
	v_rcp_f32_e32 v91, v89
	v_add_f32_e32 v89, v34, v35
	v_add_f32_e32 v89, v100, v89
	v_pk_mul_f32 v[96:97], v[0:1], v[0:1]
	v_add_f32_e32 v89, v101, v89
	v_pk_mul_f32 v[2:3], v[2:3], v[90:91]
	v_add_f32_e32 v89, v96, v89
	v_pk_mul_f32 v[90:91], v[2:3], v[2:3]
	v_add_f32_e32 v89, v97, v89
	v_add_f32_e32 v89, v90, v89
	v_add_f32_e32 v89, v91, v89
	s_nop 1
	v_add_f32_dpp v89, v89, v89 quad_perm:[1,0,3,2] row_mask:0xf bank_mask:0xf
	s_nop 1
	v_add_f32_dpp v89, v89, v89 quad_perm:[2,3,0,1] row_mask:0xf bank_mask:0xf
	s_nop 1
	v_add_f32_dpp v89, v89, v89 row_half_mirror row_mask:0xf bank_mask:0xf
	s_nop 1
	v_mov_b32_dpp v90, v89 row_mirror row_mask:0xf bank_mask:0xf
	s_and_saveexec_b64 s[22:23], vcc
	s_cbranch_execz .Ls1f3_754
	s_waitcnt lgkmcnt(0)
	v_add_f32_e32 v88, v89, v90
	v_add_f32_e32 v88, 0x358637bd, v88
	v_mul_f32_e32 v89, 0x4b800000, v88
	v_cmp_gt_f32_e32 vcc, s34, v88
	s_nop 1
	v_cndmask_b32_e32 v88, v88, v89, vcc
	v_rsq_f32_e32 v88, v88
	s_nop 0
	v_mul_f32_e32 v89, 0x45800000, v88
	v_cndmask_b32_e32 v88, v88, v89, vcc
	v_cmp_gt_u32_e32 vcc, s30, v111
	s_nop 1
	v_cndmask_b32_e32 v89, 1.0, v231, vcc
	v_mul_f32_e32 v88, v89, v88
; #define LAS __attribute__((address_space(3)))
; __device__ __forceinline__ float lo_bf(unsigned w) { return __uint_as_float(w << 16); }
; __device__ __forceinline__ float hi_bf(unsigned w) { return __uint_as_float(w & 0xffff0000u); }
; __device__ __forceinline__ unsigned pk2(float lo, float hi) { const f32x2_t v = {lo, hi}; const bf16x2_t b = __builtin_convertvector(v, bf16x2_t); return __builtin_bit_cast(unsigned, b); }
; __device__ __forceinline__ float silu_(float x) { return x * sigm(x); }
; __device__ __forceinline__ void dn_prep_item(const Args& a, LAS unsigned char* lds, int item, int tid, int wave, int lane, int& cwh, int next_item) {
;     ...
;     for (int r = 0; r < 6; ++r) { const int task = tid + NTHR * r, which = task >> 10, i = (task & 1023) >> 4, gq = task & 15;
;         const int col = 1024 + which * 512 + h * 128 + 8 * gq;
;         v4u xv[4];
; #pragma unroll
;         for (int jj = 0; jj < 4; ++jj) { const int pos = n * 64 + i - 3 + jj; xv[jj] = (v4u){0u, 0u, 0u, 0u};
;             if (pos >= 0) xv[jj] = *(const v4u*)(P + (size_t)(b * T + pos) * NIN + col); }
;         float o[8];
; #pragma unroll
;         for (int q = 0; q < 8; ++q) o[q] = 0.f;
; #pragma unroll
;         for (int jj = 0; jj < 4; ++jj) { const v4u v = xv[jj];
;             const f32x4 w0 = *(const LAS f32x4*)(cwl + (which * 4 + jj) * 128 + 8 * gq), w1 = *(const LAS f32x4*)(cwl + (which * 4 + jj) * 128 + 8 * gq + 4);
;             o[0] += w0[0] * lo_bf(v.x); o[1] += w0[1] * hi_bf(v.x); o[2] += w0[2] * lo_bf(v.y); o[3] += w0[3] * hi_bf(v.y);
;             o[4] += w1[0] * lo_bf(v.z); o[5] += w1[1] * hi_bf(v.z); o[6] += w1[2] * lo_bf(v.w); o[7] += w1[3] * hi_bf(v.w); }
;         float s = 0.f;
; #pragma unroll
;         for (int q = 0; q < 8; ++q) { o[q] = silu_(o[q]); s += o[q] * o[q]; }
;         s += __shfl_xor(s, 1); s += __shfl_xor(s, 2); s += __shfl_xor(s, 4); s += __shfl_xor(s, 8);
;         const float inv = which == 2 ? 1.0f : rsqrtf(s + EPS) * (which == 0 ? 0.08838834764831845f : 1.0f);
;         v4u w; w.x = pk2(o[0] * inv, o[1] * inv); w.y = pk2(o[2] * inv, o[3] * inv); w.z = pk2(o[4] * inv, o[5] * inv); w.w = pk2(o[6] * inv, o[7] * inv);
;         *(LAS v4u*)(lds + (which == 0 ? L_QS : which == 1 ? L_KH : L_V) + i * KS_ + 16 * gq) = w;
.Ls1f3_754:
	s_or_b64 exec, exec, s[22:23]
	v_pk_mul_f32 v[0:1], v[0:1], v[88:89] op_sel_hi:[1,0]
	v_cmp_eq_u32_e32 vcc, 1, v109
	v_cvt_pk_bf16_f32 v96, v0, v1
	v_pk_mul_f32 v[0:1], v[2:3], v[88:89] op_sel_hi:[1,0]
	s_waitcnt lgkmcnt(0)
	v_pk_mul_f32 v[90:91], v[32:33], v[88:89] op_sel_hi:[1,0]
	v_cvt_pk_bf16_f32 v97, v0, v1
	v_cndmask_b32_e64 v0, v188, 0, vcc
	v_cmp_lt_u32_e32 vcc, s31, v111
	v_cvt_pk_bf16_f32 v94, v90, v91
	v_pk_mul_f32 v[90:91], v[92:93], v[88:89] op_sel_hi:[1,0]
	v_cndmask_b32_e32 v0, v232, v0, vcc
	v_add_u32_e32 v0, 0, v0
	v_mul_u32_u24_e32 v1, 0x110, v108
	v_cvt_pk_bf16_f32 v95, v90, v91
	v_add3_u32 v0, v0, v1, v151
	ds_write_b128 v0, v[94:97]
	v_add_u32_e32 v0, 0x400, v111
	v_lshrrev_b32_e32 v109, 10, v0
	v_add_u32_e32 v0, 0x60, v218
	v_and_b32_e32 v108, 63, v0
	v_lshl_add_u32 v1, v109, 9, v36
	v_add_u32_e32 v0, s86, v108
	v_lshlrev_b32_e32 v56, 1, v1
	v_add_u32_e32 v1, s41, v0
	v_mov_b64_e32 v[2:3], s[10:11]
	v_mad_u64_u32 v[2:3], vcc, v1, s25, v[2:3]
	v_lshl_add_u64 v[2:3], v[2:3], 0, v[56:57]
	global_load_dwordx4 v[100:103], v[2:3], off
	v_add_u32_e32 v1, s42, v0
	v_mov_b64_e32 v[2:3], s[10:11]
	v_mad_u64_u32 v[2:3], vcc, v1, s25, v[2:3]
	v_lshl_add_u64 v[2:3], v[2:3], 0, v[56:57]
	global_load_dwordx4 v[92:95], v[2:3], off
	v_add_u32_e32 v2, s43, v0
	v_mov_b64_e32 v[0:1], s[10:11]
	v_mad_u64_u32 v[0:1], vcc, v2, s25, v[0:1]
	v_lshl_add_u64 v[0:1], v[0:1], 0, v[56:57]
	global_load_dwordx4 v[104:107], v[0:1], off
	v_or_b32_e32 v2, s39, v108
	v_mov_b64_e32 v[0:1], s[10:11]
	v_mad_u64_u32 v[0:1], s[22:23], v2, s25, v[0:1]
	v_lshl_add_u64 v[0:1], v[0:1], 0, v[56:57]
	global_load_dwordx4 v[88:91], v[0:1], off
	v_lshl_add_u32 v0, v114, 11, v150
	ds_read_b128 v[72:75], v0
	ds_read_b128 v[28:31], v0 offset:16
	ds_read_b128 v[76:79], v0 offset:512
	ds_read_b128 v[24:27], v0 offset:528
	ds_read_b128 v[80:83], v0 offset:1024
	ds_read_b128 v[12:15], v0 offset:1040
	ds_read_b128 v[84:87], v0 offset:1536
	ds_read_b128 v[0:3], v0 offset:1552
	s_waitcnt vmcnt(7)
	v_lshlrev_b32_e32 v32, 16, v16
	v_and_b32_e32 v33, 0xffff0000, v16
	s_waitcnt lgkmcnt(7)
	v_pk_fma_f32 v[32:33], v[72:73], v[32:33], 0 op_sel_hi:[1,1,0]
	s_waitcnt vmcnt(6)
	v_lshlrev_b32_e32 v34, 16, v8
	v_and_b32_e32 v35, 0xffff0000, v8
	s_waitcnt lgkmcnt(5)
	v_pk_fma_f32 v[32:33], v[76:77], v[34:35], v[32:33]
	s_waitcnt vmcnt(5)
	v_lshlrev_b32_e32 v34, 16, v20
	v_and_b32_e32 v35, 0xffff0000, v20
	s_waitcnt lgkmcnt(3)
	v_pk_fma_f32 v[32:33], v[80:81], v[34:35], v[32:33]
	v_lshlrev_b32_e32 v16, 16, v17
	v_and_b32_e32 v17, 0xffff0000, v17
	v_pk_fma_f32 v[16:17], v[74:75], v[16:17], 0 op_sel_hi:[1,1,0]
	v_lshlrev_b32_e32 v20, 16, v18
	v_cmp_ne_u32_e32 vcc, 2, v114
	s_waitcnt vmcnt(4)
	v_lshlrev_b32_e32 v34, 16, v4
	v_and_b32_e32 v35, 0xffff0000, v4
	s_waitcnt lgkmcnt(1)
	v_pk_fma_f32 v[32:33], v[84:85], v[34:35], v[32:33]
	s_nop 0
	v_mul_f32_e32 v4, 0xbfb8aa3b, v32
	v_exp_f32_e32 v8, v4
	v_mov_b32_e32 v4, 1.0
	v_add_f32_e32 v8, 1.0, v8
	v_rcp_f32_e32 v34, v8
	v_mul_f32_e32 v8, 0xbfb8aa3b, v33
	v_exp_f32_e32 v8, v8
	s_nop 0
	v_add_f32_e32 v8, 1.0, v8
	v_rcp_f32_e32 v35, v8
	v_lshlrev_b32_e32 v8, 16, v9
	v_and_b32_e32 v9, 0xffff0000, v9
	v_pk_fma_f32 v[8:9], v[78:79], v[8:9], v[16:17]
	v_lshlrev_b32_e32 v16, 16, v21
	v_and_b32_e32 v17, 0xffff0000, v21
	v_pk_fma_f32 v[8:9], v[82:83], v[16:17], v[8:9]
	v_lshlrev_b32_e32 v16, 16, v5
	v_and_b32_e32 v17, 0xffff0000, v5
	v_pk_fma_f32 v[8:9], v[86:87], v[16:17], v[8:9]
	v_and_b32_e32 v21, 0xffff0000, v18
	v_mul_f32_e32 v5, 0xbfb8aa3b, v8
	v_exp_f32_e32 v5, v5
	v_pk_fma_f32 v[20:21], v[28:29], v[20:21], 0 op_sel_hi:[1,1,0]
	v_lshlrev_b32_e32 v28, 16, v10
	v_and_b32_e32 v29, 0xffff0000, v10
	v_add_f32_e32 v5, 1.0, v5
	v_rcp_f32_e32 v16, v5
	v_mul_f32_e32 v5, 0xbfb8aa3b, v9
	v_exp_f32_e32 v5, v5
	v_pk_fma_f32 v[20:21], v[24:25], v[28:29], v[20:21]
	v_lshlrev_b32_e32 v24, 16, v22
	v_and_b32_e32 v25, 0xffff0000, v22
	v_pk_fma_f32 v[12:13], v[12:13], v[24:25], v[20:21]
	v_lshlrev_b32_e32 v20, 16, v6
	v_and_b32_e32 v21, 0xffff0000, v6
	v_add_f32_e32 v5, 1.0, v5
	s_waitcnt lgkmcnt(0)
	v_pk_fma_f32 v[0:1], v[0:1], v[20:21], v[12:13]
	v_rcp_f32_e32 v17, v5
	v_mul_f32_e32 v5, 0xbfb8aa3b, v0
	v_exp_f32_e32 v5, v5
	v_lshlrev_b32_e32 v18, 16, v19
	v_and_b32_e32 v19, 0xffff0000, v19
	v_pk_fma_f32 v[18:19], v[30:31], v[18:19], 0 op_sel_hi:[1,1,0]
	v_add_f32_e32 v5, 1.0, v5
	v_rcp_f32_e32 v12, v5
	v_mul_f32_e32 v5, 0xbfb8aa3b, v1
	v_exp_f32_e32 v5, v5
	v_lshlrev_b32_e32 v10, 16, v11
	v_and_b32_e32 v11, 0xffff0000, v11
	v_pk_fma_f32 v[10:11], v[26:27], v[10:11], v[18:19]
	v_lshlrev_b32_e32 v18, 16, v23
	v_and_b32_e32 v19, 0xffff0000, v23
	v_pk_fma_f32 v[10:11], v[14:15], v[18:19], v[10:11]
	v_lshlrev_b32_e32 v6, 16, v7
	v_and_b32_e32 v7, 0xffff0000, v7
	v_add_f32_e32 v5, 1.0, v5
	v_pk_fma_f32 v[2:3], v[2:3], v[6:7], v[10:11]
	v_rcp_f32_e32 v13, v5
	v_mul_f32_e32 v5, 0xbfb8aa3b, v2
	v_exp_f32_e32 v5, v5
	v_pk_mul_f32 v[32:33], v[32:33], v[34:35]
	v_pk_mul_f32 v[8:9], v[8:9], v[16:17]
	v_pk_mul_f32 v[34:35], v[32:33], v[32:33]
	v_add_f32_e32 v5, 1.0, v5
	v_rcp_f32_e32 v6, v5
	v_mul_f32_e32 v5, 0xbfb8aa3b, v3
	v_exp_f32_e32 v5, v5
	v_pk_mul_f32 v[16:17], v[8:9], v[8:9]
	v_pk_mul_f32 v[0:1], v[0:1], v[12:13]
	v_add_f32_e32 v5, 1.0, v5
	v_rcp_f32_e32 v7, v5
	v_add_f32_e32 v5, v34, v35
	v_add_f32_e32 v5, v16, v5
	v_pk_mul_f32 v[12:13], v[0:1], v[0:1]
	v_add_f32_e32 v5, v17, v5
	v_pk_mul_f32 v[2:3], v[2:3], v[6:7]
	v_add_f32_e32 v5, v12, v5
	v_pk_mul_f32 v[6:7], v[2:3], v[2:3]
	v_add_f32_e32 v5, v13, v5
	v_add_f32_e32 v5, v6, v5
	v_add_f32_e32 v5, v7, v5
	s_nop 1
	v_add_f32_dpp v5, v5, v5 quad_perm:[1,0,3,2] row_mask:0xf bank_mask:0xf
	s_nop 1
	v_add_f32_dpp v5, v5, v5 quad_perm:[2,3,0,1] row_mask:0xf bank_mask:0xf
	s_nop 1
	v_add_f32_dpp v5, v5, v5 row_half_mirror row_mask:0xf bank_mask:0xf
	s_nop 1
	v_mov_b32_dpp v6, v5 row_mirror row_mask:0xf bank_mask:0xf
	s_and_saveexec_b64 s[22:23], vcc
	s_cbranch_execz .Ls1f4_762
	s_waitcnt lgkmcnt(0)
	v_add_f32_e32 v4, v5, v6
	v_add_f32_e32 v4, 0x358637bd, v4
	v_mul_f32_e32 v5, 0x4b800000, v4
	v_cmp_gt_f32_e32 vcc, s34, v4
	s_nop 1
	v_cndmask_b32_e32 v4, v4, v5, vcc
	v_rsq_f32_e32 v4, v4
	s_nop 0
	v_mul_f32_e32 v5, 0x45800000, v4
	v_cndmask_b32_e32 v4, v4, v5, vcc
	v_cmp_gt_u32_e32 vcc, s30, v112
	s_nop 1
	v_cndmask_b32_e32 v5, 1.0, v231, vcc
	v_mul_f32_e32 v4, v5, v4
